# c22 + phase 8: next item's query rows L2-touched after the current item's last counted wait (private register)
# baseline (speedup 1.0000x reference)
.LBB0_1688:
	s_cmpk_gt_i32 s37, 0x80f
	s_cbranch_scc1 .LBB0_1687
	s_and_b32 s2, s38, 0xffffff80
	v_mbcnt_lo_u32_b32 v69, -1, 0
	v_mbcnt_hi_u32_b32 v69, -1, v69
	s_or_b32 s2, s2, s13
	v_and_b32_e32 v2, 31, v69
	v_or_b32_e32 v0, s2, v2
	v_ashrrev_i32_e32 v1, 31, v0
	s_and_b32 s11, s37, 7
	v_lshlrev_b64 v[0:1], 11, v[0:1]
	v_lshl_add_u64 v[0:1], s[4:5], 0, v[0:1]
	s_lshl_b32 s2, s11, 8
	v_lshl_add_u64 v[4:5], v[0:1], 0, s[2:3]
	s_lshl_b32 s2, s11, 1
	v_ashrrev_i32_e32 v102, 5, v69
	s_add_i32 s2, s2, s1
	s_lshl_b64 s[14:15], s[2:3], 14
	v_lshlrev_b32_e32 v0, 3, v102
	v_ashrrev_i32_e32 v1, 31, v0
	s_add_u32 s14, s17, s14
	s_waitcnt lgkmcnt(8)
	v_lshlrev_b64 v[6:7], 1, v[0:1]
	s_addc_u32 s15, s18, s15
	v_lshl_add_u64 v[0:1], s[14:15], 0, v[6:7]
	v_lshlrev_b32_e32 v64, 7, v2
	v_lshl_add_u64 v[94:95], v[0:1], 0, v[64:65]
	s_mov_b32 s11, s3
	v_lshl_add_u64 v[4:5], v[4:5], 0, s[10:11]
	v_lshl_add_u64 v[96:97], v[4:5], 0, v[6:7]
	s_mov_b32 s92, 0x800000
	s_mov_b32 s93, 0
	v_lshl_add_u64 v[186:187], v[96:97], 0, s[92:93]
	v_add_co_u32_e32 v98, vcc, s28, v94
	s_nop 1
	v_addc_co_u32_e32 v99, vcc, 0, v95, vcc
	v_add_co_u32_e32 v90, vcc, s29, v94
	s_nop 1
	v_addc_co_u32_e32 v91, vcc, 0, v95, vcc
	v_add_co_u32_e32 v100, vcc, s27, v94
	s_nop 1
	v_addc_co_u32_e32 v101, vcc, 0, v95, vcc
	global_load_dwordx4 v[104:107], v[94:95], off
	global_load_dwordx4 v[108:111], v[96:97], off
	global_load_dwordx4 v[112:115], v[96:97], off offset:32
	global_load_dwordx4 v[116:119], v[94:95], off offset:32
	global_load_dwordx4 v[120:123], v[98:99], off offset:-4096
	global_load_dwordx4 v[124:127], v[90:91], off offset:96
	global_load_dwordx4 v[128:131], v[98:99], off
	global_load_dwordx4 v[132:135], v[98:99], off offset:32
	global_load_dwordx4 v[136:139], v[90:91], off
	global_load_dwordx4 v[140:143], v[100:101], off offset:32
	global_load_dwordx4 v[144:147], v[100:101], off offset:64
	global_load_dwordx4 v[148:151], v[90:91], off offset:32
	global_load_dwordx4 v[152:155], v[94:95], off offset:64
	global_load_dwordx4 v[156:159], v[90:91], off offset:64
	global_load_dwordx4 v[160:163], v[96:97], off offset:64
	global_load_dwordx4 v[164:167], v[96:97], off offset:96
	global_load_dwordx4 v[168:171], v[94:95], off offset:96
	global_load_dwordx4 v[172:175], v[98:99], off offset:64
	global_load_dwordx4 v[176:179], v[98:99], off offset:96
	global_load_dwordx4 v[180:183], v[100:101], off offset:96
	v_lshlrev_b32_e32 v64, 2, v102
	s_nop 0
	s_waitcnt vmcnt(18)
	v_mfma_f32_32x32x16_bf16 v[32:47], v[104:107], v[108:111], 0
	s_nop 1
	s_waitcnt vmcnt(16)
	v_mfma_f32_32x32x16_bf16 v[32:47], v[116:119], v[112:115], v[32:47]
	v_cmp_lt_i32_e32 vcc, v67, v68
	s_waitcnt vmcnt(15)
	v_mfma_f32_32x32x16_bf16 v[48:63], v[120:123], v[108:111], 0
	s_waitcnt lgkmcnt(1)
	s_waitcnt vmcnt(13)
	v_mfma_f32_32x32x16_bf16 v[16:31], v[128:131], v[108:111], 0
	s_waitcnt vmcnt(12)
	v_mfma_f32_32x32x16_bf16 v[16:31], v[132:135], v[112:115], v[16:31]
	s_waitcnt vmcnt(10)
	v_mfma_f32_32x32x16_bf16 v[48:63], v[140:143], v[112:115], v[48:63]
	s_nop 0
	s_waitcnt lgkmcnt(0)
	v_mfma_f32_32x32x16_bf16 v[0:15], v[136:139], v[108:111], 0
	s_waitcnt vmcnt(8)
	v_mfma_f32_32x32x16_bf16 v[0:15], v[148:151], v[112:115], v[0:15]
	s_nop 0
	s_waitcnt vmcnt(5)
	v_mfma_f32_32x32x16_bf16 v[32:47], v[152:155], v[160:163], v[32:47]
	v_mfma_f32_32x32x16_bf16 v[48:63], v[144:147], v[160:163], v[48:63]
	v_add_u32_e32 v98, 51, v64
	v_add_u32_e32 v99, 56, v64
	v_mfma_f32_32x32x16_bf16 v[0:15], v[156:159], v[160:163], v[0:15]
	v_add_u32_e32 v90, 16, v64
	v_add_u32_e32 v91, 17, v64
	v_add_u32_e32 v92, 18, v64
	v_add_u32_e32 v93, 19, v64
	s_waitcnt vmcnt(3)
	v_mfma_f32_32x32x16_bf16 v[32:47], v[168:171], v[164:167], v[32:47]
	v_add_u32_e32 v94, 32, v64
	v_add_u32_e32 v95, 40, v64
	v_add_u32_e32 v96, 41, v64
	v_add_u32_e32 v97, 50, v64
	v_mfma_f32_32x32x16_bf16 v[0:15], v[124:127], v[164:167], v[0:15]
	s_nop 6
	v_and_b32_e32 v33, 0xffffff80, v33
	v_and_or_b32 v32, v32, s26, v64
	v_and_b32_e32 v34, 0xffffff80, v34
	v_and_b32_e32 v35, 0xffffff80, v35
	v_or3_b32 v33, v64, v33, 1
	v_or3_b32 v34, v64, v34, 2
	v_or3_b32 v35, v64, v35, 3
	v_and_or_b32 v40, v40, s26, v90
	v_and_or_b32 v41, v41, s26, v91
	v_and_or_b32 v42, v42, s26, v92
	v_and_or_b32 v43, v43, s26, v93
	s_waitcnt vmcnt(2)
	v_mfma_f32_32x32x16_bf16 v[16:31], v[172:175], v[160:163], v[16:31]
	v_add_u32_e32 v82, 8, v64
	v_add_u32_e32 v83, 9, v64
	v_and_or_b32 v36, v36, s26, v82
	v_add_u32_e32 v84, 10, v64
	v_and_or_b32 v37, v37, s26, v83
	v_add_u32_e32 v85, 11, v64
	s_waitcnt vmcnt(1)
	v_mfma_f32_32x32x16_bf16 v[16:31], v[176:179], v[164:167], v[16:31]
	v_and_or_b32 v38, v38, s26, v84
	v_and_or_b32 v39, v39, s26, v85
	v_add_u32_e32 v86, 42, v64
	v_add_u32_e32 v87, 43, v64
	v_add_u32_e32 v88, 48, v64
	v_add_u32_e32 v89, 49, v64
	s_waitcnt vmcnt(0)
	v_mfma_f32_32x32x16_bf16 v[48:63], v[180:183], v[164:167], v[48:63]
	s_add_i32 s94, s37, s0
	s_cmpk_gt_i32 s94, 0x80f
	s_cbranch_scc1 .Lp8_nt
	global_load_dword v188, v[186:187], off
.Lp8_nt:
	v_add_u32_e32 v70, 24, v64
	v_and_or_b32 v44, v44, s26, v70
	v_add_u32_e32 v70, 57, v64
	v_add_u32_e32 v71, 25, v64
	v_add_u32_e32 v72, 26, v64
	v_and_or_b32 v45, v45, s26, v71
	v_add_u32_e32 v73, 27, v64
	s_nop 4
	v_and_or_b32 v61, v61, s26, v70
	v_add_u32_e32 v70, 58, v64
	v_and_or_b32 v62, v62, s26, v70
	v_add_u32_e32 v70, 59, v64
	v_and_or_b32 v63, v63, s26, v70
	v_add_u32_e32 v70, 64, v64
	v_and_or_b32 v71, v16, s26, v70
	v_and_b32_e32 v16, 0xffffff80, v17
	v_and_or_b32 v46, v46, s26, v72
	v_or3_b32 v72, v70, v16, 1
	v_and_b32_e32 v16, 0xffffff80, v18
	v_and_or_b32 v47, v47, s26, v73
	v_or3_b32 v73, v70, v16, 2
	v_and_b32_e32 v16, 0xffffff80, v19
	v_or3_b32 v70, v70, v16, 3
	v_add_u32_e32 v16, 0x48, v64
	v_and_or_b32 v74, v20, s26, v16
	v_add_u32_e32 v16, 0x49, v64
	v_and_or_b32 v75, v21, s26, v16
	v_add_u32_e32 v16, 0x4a, v64
	v_and_or_b32 v76, v22, s26, v16
	v_add_u32_e32 v16, 0x4b, v64
	v_and_or_b32 v77, v23, s26, v16
	v_add_u32_e32 v16, 0x50, v64
	v_and_or_b32 v78, v24, s26, v16
	v_add_u32_e32 v16, 0x51, v64
	v_and_or_b32 v79, v25, s26, v16
	v_add_u32_e32 v16, 0x52, v64
	v_and_or_b32 v80, v26, s26, v16
	v_add_u32_e32 v16, 0x53, v64
	v_and_or_b32 v81, v27, s26, v16
	v_add_u32_e32 v16, 0x58, v64
	v_and_or_b32 v82, v28, s26, v16
	v_add_u32_e32 v16, 0x59, v64
	v_and_or_b32 v83, v29, s26, v16
	v_add_u32_e32 v16, 0x5a, v64
	v_and_or_b32 v84, v30, s26, v16
	v_add_u32_e32 v16, 0x5b, v64
	v_add_u32_e32 v18, 0x60, v64
	v_and_or_b32 v85, v31, s26, v16
	v_and_or_b32 v16, v0, s26, v18
	v_and_b32_e32 v0, 0xffffff80, v1
	v_or3_b32 v17, v18, v0, 1
	v_and_b32_e32 v0, 0xffffff80, v2
	v_and_b32_e32 v1, 0xffffff80, v3
	v_or3_b32 v0, v18, v0, 2
	v_or3_b32 v18, v18, v1, 3
	v_add_u32_e32 v1, 0x68, v64
	v_add_u32_e32 v2, 0x69, v64
	v_add_u32_e32 v3, 0x6b, v64
	v_and_or_b32 v1, v4, s26, v1
	v_and_or_b32 v19, v5, s26, v2
	v_add_u32_e32 v2, 0x6a, v64
	v_and_or_b32 v7, v7, s26, v3
	v_add_u32_e32 v3, 0x70, v64
	v_add_u32_e32 v4, 0x71, v64
	v_add_u32_e32 v5, 0x73, v64
	v_and_or_b32 v2, v6, s26, v2
	v_and_or_b32 v3, v8, s26, v3
	v_and_or_b32 v8, v9, s26, v4
	v_add_u32_e32 v4, 0x72, v64
	v_and_or_b32 v9, v11, s26, v5
	v_add_u32_e32 v5, 0x78, v64
	v_add_u32_e32 v6, 0x79, v64
	v_and_or_b32 v4, v10, s26, v4
	v_and_or_b32 v5, v12, s26, v5
	v_and_or_b32 v10, v13, s26, v6
	v_add_u32_e32 v6, 0x7a, v64
	v_add_u32_e32 v11, 0x7b, v64
	v_max_f32_e32 v12, v32, v32
	v_max_f32_e32 v13, v33, v33
	v_and_or_b32 v6, v14, s26, v6
	v_and_or_b32 v11, v15, s26, v11
	v_min_f32_e32 v14, v12, v13
	v_max_f32_e32 v12, v12, v13
	v_max_f32_e32 v13, v35, v35
	v_max_f32_e32 v15, v34, v34
	v_and_b32_e32 v49, 0xffffff80, v49
	v_max_f32_e32 v20, v15, v13
	v_min_f32_e32 v13, v15, v13
	v_max_f32_e32 v15, v37, v37
	v_max_f32_e32 v21, v36, v36
	v_and_or_b32 v48, v48, s26, v94
	v_and_b32_e32 v50, 0xffffff80, v50
	v_and_b32_e32 v51, 0xffffff80, v51
	v_or3_b32 v49, v94, v49, 1
	v_min_f32_e32 v22, v21, v15
	v_max_f32_e32 v15, v21, v15
	v_max_f32_e32 v21, v39, v39
	v_max_f32_e32 v23, v38, v38
	v_or3_b32 v50, v94, v50, 2
	v_or3_b32 v51, v94, v51, 3
	v_max_f32_e32 v24, v23, v21
	v_min_f32_e32 v21, v23, v21
	v_max_f32_e32 v23, v41, v41
	v_max_f32_e32 v25, v40, v40
	v_max_f32_e32 v40, v48, v48
	v_max_f32_e32 v41, v49, v49
	v_max_f32_e32 v64, v71, v71
	v_max_f32_e32 v71, v72, v72
	v_and_or_b32 v52, v52, s26, v95
	v_and_or_b32 v53, v53, s26, v96
	v_min_f32_e32 v26, v25, v23
	v_max_f32_e32 v23, v25, v23
	v_max_f32_e32 v25, v43, v43
	v_max_f32_e32 v27, v42, v42
	v_min_f32_e32 v42, v40, v41
	v_max_f32_e32 v40, v40, v41
	v_max_f32_e32 v41, v51, v51
	v_max_f32_e32 v43, v50, v50
	v_min_f32_e32 v72, v64, v71
	v_max_f32_e32 v64, v64, v71
	v_max_f32_e32 v70, v70, v70
	v_max_f32_e32 v71, v73, v73
	v_max_f32_e32 v16, v16, v16
	v_max_f32_e32 v17, v17, v17
	v_and_or_b32 v54, v54, s26, v86
	v_and_or_b32 v55, v55, s26, v87
	v_max_f32_e32 v28, v27, v25
	v_min_f32_e32 v25, v27, v25
	v_max_f32_e32 v27, v45, v45
	v_max_f32_e32 v29, v44, v44
	v_max_f32_e32 v44, v43, v41
	v_min_f32_e32 v41, v43, v41
	v_max_f32_e32 v43, v53, v53
	v_max_f32_e32 v45, v52, v52
	v_max_f32_e32 v73, v71, v70
	v_min_f32_e32 v70, v71, v70
	v_max_f32_e32 v71, v75, v75
	v_max_f32_e32 v74, v74, v74
	v_min_f32_e32 v93, v16, v17
	v_max_f32_e32 v16, v16, v17
	v_max_f32_e32 v17, v18, v18
	v_max_f32_e32 v0, v0, v0
	v_and_or_b32 v56, v56, s26, v88
	v_and_or_b32 v57, v57, s26, v89
	v_min_f32_e32 v30, v29, v27
	v_max_f32_e32 v27, v29, v27
	v_max_f32_e32 v29, v47, v47
	v_max_f32_e32 v31, v46, v46
	v_min_f32_e32 v46, v45, v43
	v_max_f32_e32 v43, v45, v43
	v_max_f32_e32 v45, v55, v55
	v_max_f32_e32 v47, v54, v54
	v_min_f32_e32 v75, v74, v71
	v_max_f32_e32 v71, v74, v71
	v_max_f32_e32 v74, v77, v77
	v_max_f32_e32 v76, v76, v76
	v_max_f32_e32 v18, v0, v17
	v_min_f32_e32 v0, v0, v17
	v_max_f32_e32 v17, v19, v19
	v_max_f32_e32 v1, v1, v1
	v_max_f32_e32 v7, v7, v7
	v_max_f32_e32 v2, v2, v2
	v_and_or_b32 v58, v58, s26, v97
	v_and_or_b32 v59, v59, s26, v98
	v_max_f32_e32 v48, v47, v45
	v_min_f32_e32 v45, v47, v45
	v_max_f32_e32 v47, v57, v57
	v_max_f32_e32 v49, v56, v56
	v_max_f32_e32 v77, v76, v74
	v_min_f32_e32 v74, v76, v74
	v_max_f32_e32 v76, v79, v79
	v_max_f32_e32 v78, v78, v78
	v_min_f32_e32 v19, v1, v17
	v_max_f32_e32 v1, v1, v17
	v_max_f32_e32 v17, v2, v7
	v_min_f32_e32 v2, v2, v7
	v_max_f32_e32 v7, v8, v8
	v_max_f32_e32 v3, v3, v3
	v_and_or_b32 v60, v60, s26, v99
	v_min_f32_e32 v50, v49, v47
	v_max_f32_e32 v47, v49, v47
	v_max_f32_e32 v49, v59, v59
	v_max_f32_e32 v51, v58, v58
	v_min_f32_e32 v79, v78, v76
	v_max_f32_e32 v76, v78, v76
	v_max_f32_e32 v78, v81, v81
	v_max_f32_e32 v80, v80, v80
	v_min_f32_e32 v8, v3, v7
	v_max_f32_e32 v3, v3, v7
	v_max_f32_e32 v7, v9, v9
	v_max_f32_e32 v4, v4, v4
	v_max_f32_e32 v52, v51, v49
	v_min_f32_e32 v49, v51, v49
	v_max_f32_e32 v51, v61, v61
	v_max_f32_e32 v53, v60, v60
	v_max_f32_e32 v81, v80, v78
	v_min_f32_e32 v78, v80, v78
	v_max_f32_e32 v80, v83, v83
	v_max_f32_e32 v82, v82, v82
	v_max_f32_e32 v9, v4, v7
	v_min_f32_e32 v4, v4, v7
	v_max_f32_e32 v7, v10, v10
	v_max_f32_e32 v5, v5, v5
	v_min_f32_e32 v54, v53, v51
	v_max_f32_e32 v51, v53, v51
	v_max_f32_e32 v53, v63, v63
	v_max_f32_e32 v55, v62, v62
	v_min_f32_e32 v83, v82, v80
	v_max_f32_e32 v80, v82, v80
	v_max_f32_e32 v82, v85, v85
	v_max_f32_e32 v84, v84, v84
	v_min_f32_e32 v10, v5, v7
	v_max_f32_e32 v5, v5, v7
	v_max_f32_e32 v7, v11, v11
	v_max_f32_e32 v6, v6, v6
	v_max_f32_e32 v32, v31, v29
	v_min_f32_e32 v29, v31, v29
	v_max_f32_e32 v56, v55, v53
	v_min_f32_e32 v53, v55, v53
	v_max_f32_e32 v85, v84, v82
	v_min_f32_e32 v82, v84, v82
	v_max_f32_e32 v11, v6, v7
	v_min_f32_e32 v6, v6, v7
	v_min_f32_e32 v31, v12, v13
	v_max_f32_e32 v12, v12, v13
	v_min_f32_e32 v13, v14, v20
	v_max_f32_e32 v14, v14, v20
	v_max_f32_e32 v20, v15, v21
	v_min_f32_e32 v15, v15, v21
	v_max_f32_e32 v21, v22, v24
	v_min_f32_e32 v22, v22, v24
	v_min_f32_e32 v24, v23, v25
	v_max_f32_e32 v23, v23, v25
	v_min_f32_e32 v25, v26, v28
	v_max_f32_e32 v26, v26, v28
	v_max_f32_e32 v28, v27, v29
	v_min_f32_e32 v27, v27, v29
	v_max_f32_e32 v29, v30, v32
	v_min_f32_e32 v30, v30, v32
	v_min_f32_e32 v55, v40, v41
	v_max_f32_e32 v40, v40, v41
	v_min_f32_e32 v41, v42, v44
	v_max_f32_e32 v42, v42, v44
	v_max_f32_e32 v44, v43, v45
	v_min_f32_e32 v43, v43, v45
	v_max_f32_e32 v45, v46, v48
	v_min_f32_e32 v46, v46, v48
	v_min_f32_e32 v48, v47, v49
	v_max_f32_e32 v47, v47, v49
	v_min_f32_e32 v49, v50, v52
	v_max_f32_e32 v50, v50, v52
	v_max_f32_e32 v52, v51, v53
	v_min_f32_e32 v51, v51, v53
	v_max_f32_e32 v53, v54, v56
	v_min_f32_e32 v54, v54, v56
	v_min_f32_e32 v84, v64, v70
	v_max_f32_e32 v64, v64, v70
	v_min_f32_e32 v70, v72, v73
	v_max_f32_e32 v72, v72, v73
	v_max_f32_e32 v73, v71, v74
	v_min_f32_e32 v71, v71, v74
	v_max_f32_e32 v74, v75, v77
	v_min_f32_e32 v75, v75, v77
	v_min_f32_e32 v77, v76, v78
	v_max_f32_e32 v76, v76, v78
	v_min_f32_e32 v78, v79, v81
	v_max_f32_e32 v79, v79, v81
	v_max_f32_e32 v81, v80, v82
	v_min_f32_e32 v80, v80, v82
	v_max_f32_e32 v82, v83, v85
	v_min_f32_e32 v83, v83, v85
	v_min_f32_e32 v7, v16, v0
	v_max_f32_e32 v0, v16, v0
	v_min_f32_e32 v16, v93, v18
	v_max_f32_e32 v18, v93, v18
	v_max_f32_e32 v93, v1, v2
	v_min_f32_e32 v1, v1, v2
	v_max_f32_e32 v2, v19, v17
	v_min_f32_e32 v17, v19, v17
	v_min_f32_e32 v19, v3, v4
	v_max_f32_e32 v3, v3, v4
	v_min_f32_e32 v4, v8, v9
	v_max_f32_e32 v8, v8, v9
	v_max_f32_e32 v9, v5, v6
	v_min_f32_e32 v5, v5, v6
	v_max_f32_e32 v6, v10, v11
	v_min_f32_e32 v10, v10, v11
	v_min_f32_e32 v32, v12, v14
	v_max_f32_e32 v12, v12, v14
	v_min_f32_e32 v14, v31, v13
	v_max_f32_e32 v13, v31, v13
	v_max_f32_e32 v31, v15, v22
	v_min_f32_e32 v15, v15, v22
	v_max_f32_e32 v22, v20, v21
	v_min_f32_e32 v20, v20, v21
	v_min_f32_e32 v21, v23, v26
	v_max_f32_e32 v23, v23, v26
	v_min_f32_e32 v26, v24, v25
	v_max_f32_e32 v24, v24, v25
	v_max_f32_e32 v25, v27, v30
	v_min_f32_e32 v27, v27, v30
	v_max_f32_e32 v30, v28, v29
	v_min_f32_e32 v28, v28, v29
	v_min_f32_e32 v56, v40, v42
	v_max_f32_e32 v40, v40, v42
	v_min_f32_e32 v42, v55, v41
	v_max_f32_e32 v41, v55, v41
	v_max_f32_e32 v55, v43, v46
	v_min_f32_e32 v43, v43, v46
	v_max_f32_e32 v46, v44, v45
	v_min_f32_e32 v44, v44, v45
	v_min_f32_e32 v45, v47, v50
	v_max_f32_e32 v47, v47, v50
	v_min_f32_e32 v50, v48, v49
	v_max_f32_e32 v48, v48, v49
	v_max_f32_e32 v49, v51, v54
	v_min_f32_e32 v51, v51, v54
	v_max_f32_e32 v54, v52, v53
	v_min_f32_e32 v52, v52, v53
	v_min_f32_e32 v85, v64, v72
	v_max_f32_e32 v64, v64, v72
	v_min_f32_e32 v72, v84, v70
	v_max_f32_e32 v70, v84, v70
	v_max_f32_e32 v84, v71, v75
	v_min_f32_e32 v71, v71, v75
	v_max_f32_e32 v75, v73, v74
	v_min_f32_e32 v73, v73, v74
	v_min_f32_e32 v74, v76, v79
	v_max_f32_e32 v76, v76, v79
	v_min_f32_e32 v79, v77, v78
	v_max_f32_e32 v77, v77, v78
	v_max_f32_e32 v78, v80, v83
	v_min_f32_e32 v80, v80, v83
	v_max_f32_e32 v83, v81, v82
	v_min_f32_e32 v81, v81, v82
	v_min_f32_e32 v11, v0, v18
	v_max_f32_e32 v0, v0, v18
	v_min_f32_e32 v18, v7, v16
	v_max_f32_e32 v7, v7, v16
	v_max_f32_e32 v16, v1, v17
	v_min_f32_e32 v1, v1, v17
	v_max_f32_e32 v17, v93, v2
	v_min_f32_e32 v2, v93, v2
	v_min_f32_e32 v93, v3, v8
	v_max_f32_e32 v3, v3, v8
	v_min_f32_e32 v8, v19, v4
	v_max_f32_e32 v4, v19, v4
	v_max_f32_e32 v19, v5, v10
	v_min_f32_e32 v5, v5, v10
	v_max_f32_e32 v10, v9, v6
	v_min_f32_e32 v6, v9, v6
	v_min_f32_e32 v29, v12, v15
	v_max_f32_e32 v12, v12, v15
	v_min_f32_e32 v15, v32, v31
	v_max_f32_e32 v31, v32, v31
	v_min_f32_e32 v32, v13, v20
	v_max_f32_e32 v13, v13, v20
	v_min_f32_e32 v20, v14, v22
	v_max_f32_e32 v14, v14, v22
	v_max_f32_e32 v22, v23, v27
	v_min_f32_e32 v23, v23, v27
	v_max_f32_e32 v27, v21, v25
	v_min_f32_e32 v21, v21, v25
	v_max_f32_e32 v25, v24, v28
	v_min_f32_e32 v24, v24, v28
	v_max_f32_e32 v28, v26, v30
	v_min_f32_e32 v26, v26, v30
	v_min_f32_e32 v53, v40, v43
	v_max_f32_e32 v40, v40, v43
	v_min_f32_e32 v43, v56, v55
	v_max_f32_e32 v55, v56, v55
	v_min_f32_e32 v56, v41, v44
	v_max_f32_e32 v41, v41, v44
	v_min_f32_e32 v44, v42, v46
	v_max_f32_e32 v42, v42, v46
	v_max_f32_e32 v46, v47, v51
	v_min_f32_e32 v47, v47, v51
	v_max_f32_e32 v51, v45, v49
	v_min_f32_e32 v45, v45, v49
	v_max_f32_e32 v49, v48, v52
	v_min_f32_e32 v48, v48, v52
	v_max_f32_e32 v52, v50, v54
	v_min_f32_e32 v50, v50, v54
	v_min_f32_e32 v82, v64, v71
	v_max_f32_e32 v64, v64, v71
	v_min_f32_e32 v71, v85, v84
	v_max_f32_e32 v84, v85, v84
	v_min_f32_e32 v85, v70, v73
	v_max_f32_e32 v70, v70, v73
	v_min_f32_e32 v73, v72, v75
	v_max_f32_e32 v72, v72, v75
	v_max_f32_e32 v75, v76, v80
	v_min_f32_e32 v76, v76, v80
	v_max_f32_e32 v80, v74, v78
	v_min_f32_e32 v74, v74, v78
	v_max_f32_e32 v78, v77, v81
	v_min_f32_e32 v77, v77, v81
	v_max_f32_e32 v81, v79, v83
	v_min_f32_e32 v79, v79, v83
	v_min_f32_e32 v9, v0, v1
	v_max_f32_e32 v0, v0, v1
	v_min_f32_e32 v1, v11, v16
	v_max_f32_e32 v11, v11, v16
	v_min_f32_e32 v16, v7, v2
	v_max_f32_e32 v2, v7, v2
	v_min_f32_e32 v7, v18, v17
	v_max_f32_e32 v17, v18, v17
	v_max_f32_e32 v18, v3, v5
	v_min_f32_e32 v3, v3, v5
	v_max_f32_e32 v5, v93, v19
	v_min_f32_e32 v19, v93, v19
	v_max_f32_e32 v93, v4, v6
	v_min_f32_e32 v4, v4, v6
	v_max_f32_e32 v6, v8, v10
	v_min_f32_e32 v8, v8, v10
	v_min_f32_e32 v30, v12, v13
	v_max_f32_e32 v12, v12, v13
	v_min_f32_e32 v13, v31, v14
	v_max_f32_e32 v14, v31, v14
	v_min_f32_e32 v31, v29, v32
	v_max_f32_e32 v29, v29, v32
	v_min_f32_e32 v32, v15, v20
	v_max_f32_e32 v15, v15, v20
	v_max_f32_e32 v20, v23, v24
	v_min_f32_e32 v23, v23, v24
	v_max_f32_e32 v24, v21, v26
	v_min_f32_e32 v21, v21, v26
	v_max_f32_e32 v26, v22, v25
	v_min_f32_e32 v22, v22, v25
	v_max_f32_e32 v25, v27, v28
	v_min_f32_e32 v27, v27, v28
	v_min_f32_e32 v54, v40, v41
	v_max_f32_e32 v40, v40, v41
	v_min_f32_e32 v41, v55, v42
	v_max_f32_e32 v42, v55, v42
	v_min_f32_e32 v55, v53, v56
	v_max_f32_e32 v53, v53, v56
	v_min_f32_e32 v56, v43, v44
	v_max_f32_e32 v43, v43, v44
	v_max_f32_e32 v44, v47, v48
	v_min_f32_e32 v47, v47, v48
	v_max_f32_e32 v48, v45, v50
	v_min_f32_e32 v45, v45, v50
	v_max_f32_e32 v50, v46, v49
	v_min_f32_e32 v46, v46, v49
	v_max_f32_e32 v49, v51, v52
	v_min_f32_e32 v51, v51, v52
	v_min_f32_e32 v83, v64, v70
	v_max_f32_e32 v64, v64, v70
	v_min_f32_e32 v70, v84, v72
	v_max_f32_e32 v72, v84, v72
	v_min_f32_e32 v84, v82, v85
	v_max_f32_e32 v82, v82, v85
	v_min_f32_e32 v85, v71, v73
	v_max_f32_e32 v71, v71, v73
	v_max_f32_e32 v73, v76, v77
	v_min_f32_e32 v76, v76, v77
	v_max_f32_e32 v77, v74, v79
	v_min_f32_e32 v74, v74, v79
	v_max_f32_e32 v79, v75, v78
	v_min_f32_e32 v75, v75, v78
	v_max_f32_e32 v78, v80, v81
	v_min_f32_e32 v80, v80, v81
	v_min_f32_e32 v10, v0, v2
	v_max_f32_e32 v0, v0, v2
	v_min_f32_e32 v2, v11, v17
	v_max_f32_e32 v11, v11, v17
	v_min_f32_e32 v17, v9, v16
	v_max_f32_e32 v9, v9, v16
	v_min_f32_e32 v16, v1, v7
	v_max_f32_e32 v1, v1, v7
	v_max_f32_e32 v7, v3, v4
	v_min_f32_e32 v3, v3, v4
	v_max_f32_e32 v4, v19, v8
	v_min_f32_e32 v8, v19, v8
	v_max_f32_e32 v19, v18, v93
	v_min_f32_e32 v18, v18, v93
	v_max_f32_e32 v93, v5, v6
	v_min_f32_e32 v5, v5, v6
	v_min_f32_e32 v28, v12, v14
	v_max_f32_e32 v12, v12, v14
	v_min_f32_e32 v14, v30, v13
	v_max_f32_e32 v13, v30, v13
	v_min_f32_e32 v30, v29, v15
	v_max_f32_e32 v15, v29, v15
	v_min_f32_e32 v29, v31, v32
	v_max_f32_e32 v31, v31, v32
	v_max_f32_e32 v32, v23, v21
	v_min_f32_e32 v21, v23, v21
	v_max_f32_e32 v23, v20, v24
	v_min_f32_e32 v20, v20, v24
	v_max_f32_e32 v24, v22, v27
	v_min_f32_e32 v22, v22, v27
	v_max_f32_e32 v27, v26, v25
	v_min_f32_e32 v25, v26, v25
	v_min_f32_e32 v52, v40, v42
	v_max_f32_e32 v40, v40, v42
	v_min_f32_e32 v42, v54, v41
	v_max_f32_e32 v41, v54, v41
	v_min_f32_e32 v54, v53, v43
	v_max_f32_e32 v43, v53, v43
	v_min_f32_e32 v53, v55, v56
	v_max_f32_e32 v55, v55, v56
	v_max_f32_e32 v56, v47, v45
	v_min_f32_e32 v45, v47, v45
	v_max_f32_e32 v47, v44, v48
	v_min_f32_e32 v44, v44, v48
	v_max_f32_e32 v48, v46, v51
	v_min_f32_e32 v46, v46, v51
	v_max_f32_e32 v51, v50, v49
	v_min_f32_e32 v49, v50, v49
	v_min_f32_e32 v81, v64, v72
	v_max_f32_e32 v64, v64, v72
	v_min_f32_e32 v72, v83, v70
	v_max_f32_e32 v70, v83, v70
	v_min_f32_e32 v83, v82, v71
	v_max_f32_e32 v71, v82, v71
	v_min_f32_e32 v82, v84, v85
	v_max_f32_e32 v84, v84, v85
	v_max_f32_e32 v85, v76, v74
	v_min_f32_e32 v74, v76, v74
	v_max_f32_e32 v76, v73, v77
	v_min_f32_e32 v73, v73, v77
	v_max_f32_e32 v77, v75, v80
	v_min_f32_e32 v75, v75, v80
	v_max_f32_e32 v80, v79, v78
	v_min_f32_e32 v78, v79, v78
	v_min_f32_e32 v6, v0, v11
	v_max_f32_e32 v0, v0, v11
	v_min_f32_e32 v11, v10, v2
	v_max_f32_e32 v2, v10, v2
	v_min_f32_e32 v10, v9, v1
	v_max_f32_e32 v1, v9, v1
	v_min_f32_e32 v9, v17, v16
	v_max_f32_e32 v16, v17, v16
	v_max_f32_e32 v17, v3, v8
	v_min_f32_e32 v3, v3, v8
	v_max_f32_e32 v8, v7, v4
	v_min_f32_e32 v4, v7, v4
	v_max_f32_e32 v7, v18, v5
	v_min_f32_e32 v5, v18, v5
	v_max_f32_e32 v18, v19, v93
	v_min_f32_e32 v19, v19, v93
	v_min_f32_e32 v26, v12, v21
	v_max_f32_e32 v12, v12, v21
	v_min_f32_e32 v21, v28, v32
	v_max_f32_e32 v28, v28, v32
	v_min_f32_e32 v32, v13, v20
	v_max_f32_e32 v13, v13, v20
	v_min_f32_e32 v20, v14, v23
	v_max_f32_e32 v14, v14, v23
	v_min_f32_e32 v23, v15, v22
	v_max_f32_e32 v15, v15, v22
	v_min_f32_e32 v22, v30, v24
	v_max_f32_e32 v24, v30, v24
	v_min_f32_e32 v30, v31, v25
	v_max_f32_e32 v25, v31, v25
	v_min_f32_e32 v31, v29, v27
	v_max_f32_e32 v27, v29, v27
	v_min_f32_e32 v50, v40, v45
	v_max_f32_e32 v40, v40, v45
	v_min_f32_e32 v45, v52, v56
	v_max_f32_e32 v52, v52, v56
	v_min_f32_e32 v56, v41, v44
	v_max_f32_e32 v41, v41, v44
	v_min_f32_e32 v44, v42, v47
	v_max_f32_e32 v42, v42, v47
	v_min_f32_e32 v47, v43, v46
	v_max_f32_e32 v43, v43, v46
	v_min_f32_e32 v46, v54, v48
	v_max_f32_e32 v48, v54, v48
	v_min_f32_e32 v54, v55, v49
	v_max_f32_e32 v49, v55, v49
	v_min_f32_e32 v55, v53, v51
	v_max_f32_e32 v51, v53, v51
	v_min_f32_e32 v79, v64, v74
	v_max_f32_e32 v64, v64, v74
	v_min_f32_e32 v74, v81, v85
	v_max_f32_e32 v81, v81, v85
	v_min_f32_e32 v85, v70, v73
	v_max_f32_e32 v70, v70, v73
	v_min_f32_e32 v73, v72, v76
	v_max_f32_e32 v72, v72, v76
	v_min_f32_e32 v76, v71, v75
	v_max_f32_e32 v71, v71, v75
	v_min_f32_e32 v75, v83, v77
	v_max_f32_e32 v77, v83, v77
	v_min_f32_e32 v83, v84, v78
	v_max_f32_e32 v78, v84, v78
	v_min_f32_e32 v84, v82, v80
	v_max_f32_e32 v80, v82, v80
	v_min_f32_e32 v93, v0, v3
	v_max_f32_e32 v0, v0, v3
	v_min_f32_e32 v3, v6, v17
	v_max_f32_e32 v6, v6, v17
	v_min_f32_e32 v17, v2, v4
	v_max_f32_e32 v2, v2, v4
	v_min_f32_e32 v4, v11, v8
	v_max_f32_e32 v8, v11, v8
	v_min_f32_e32 v11, v1, v5
	v_max_f32_e32 v1, v1, v5
	v_min_f32_e32 v5, v10, v7
	v_max_f32_e32 v7, v10, v7
	v_min_f32_e32 v10, v16, v19
	v_max_f32_e32 v16, v16, v19
	v_min_f32_e32 v19, v9, v18
	v_max_f32_e32 v9, v9, v18
	v_min_f32_e32 v33, v12, v15
	v_max_f32_e32 v15, v12, v15
	v_min_f32_e32 v34, v28, v24
	v_max_f32_e32 v24, v28, v24
	v_min_f32_e32 v28, v13, v25
	v_max_f32_e32 v13, v13, v25
	v_min_f32_e32 v25, v14, v27
	v_max_f32_e32 v14, v14, v27
	v_min_f32_e32 v27, v26, v23
	v_max_f32_e32 v26, v26, v23
	v_min_f32_e32 v35, v21, v22
	v_max_f32_e32 v36, v21, v22
	v_min_f32_e32 v37, v32, v30
	v_max_f32_e32 v22, v32, v30
	v_min_f32_e32 v32, v20, v31
	v_max_f32_e32 v31, v20, v31
	v_min_f32_e32 v53, v40, v43
	v_max_f32_e32 v40, v40, v43
	v_min_f32_e32 v43, v52, v48
	v_max_f32_e32 v48, v52, v48
	v_min_f32_e32 v52, v41, v49
	v_max_f32_e32 v41, v41, v49
	v_min_f32_e32 v49, v42, v51
	v_max_f32_e32 v42, v42, v51
	v_min_f32_e32 v51, v50, v47
	v_max_f32_e32 v47, v50, v47
	v_min_f32_e32 v50, v45, v46
	v_max_f32_e32 v45, v45, v46
	v_min_f32_e32 v46, v56, v54
	v_max_f32_e32 v54, v56, v54
	v_min_f32_e32 v56, v44, v55
	v_max_f32_e32 v44, v44, v55
	v_min_f32_e32 v82, v64, v71
	v_max_f32_e32 v64, v64, v71
	v_min_f32_e32 v71, v81, v77
	v_max_f32_e32 v77, v81, v77
	v_min_f32_e32 v81, v70, v78
	v_max_f32_e32 v70, v70, v78
	v_min_f32_e32 v78, v72, v80
	v_max_f32_e32 v72, v72, v80
	v_min_f32_e32 v80, v79, v76
	v_max_f32_e32 v76, v79, v76
	v_min_f32_e32 v79, v74, v75
	v_max_f32_e32 v74, v74, v75
	v_min_f32_e32 v75, v85, v83
	v_max_f32_e32 v83, v85, v83
	v_min_f32_e32 v85, v73, v84
	v_max_f32_e32 v73, v73, v84
	v_min_f32_e32 v18, v0, v1
	v_max_f32_e32 v0, v0, v1
	v_min_f32_e32 v1, v6, v7
	v_max_f32_e32 v6, v6, v7
	v_min_f32_e32 v7, v2, v16
	v_max_f32_e32 v2, v2, v16
	v_min_f32_e32 v16, v8, v9
	v_max_f32_e32 v8, v8, v9
	v_min_f32_e32 v9, v93, v11
	v_max_f32_e32 v11, v93, v11
	v_min_f32_e32 v93, v3, v5
	v_max_f32_e32 v3, v3, v5
	v_min_f32_e32 v5, v17, v10
	v_max_f32_e32 v10, v17, v10
	v_min_f32_e32 v17, v4, v19
	v_max_f32_e32 v4, v4, v19
	v_min_f32_e32 v12, v15, v13
	v_max_f32_e32 v23, v15, v13
	v_min_f32_e32 v20, v24, v14
	v_max_f32_e32 v29, v24, v14
	v_min_f32_e32 v13, v33, v28
	v_max_f32_e32 v24, v33, v28
	v_min_f32_e32 v21, v34, v25
	v_max_f32_e32 v30, v34, v25
	v_min_f32_e32 v14, v26, v22
	v_max_f32_e32 v25, v26, v22
	v_min_f32_e32 v22, v36, v31
	v_max_f32_e32 v31, v36, v31
	v_min_f32_e32 v15, v27, v37
	v_max_f32_e32 v26, v27, v37
	v_max_f32_e32 v28, v35, v32
	v_min_f32_e32 v27, v35, v32
	v_min_f32_e32 v55, v40, v41
	v_max_f32_e32 v40, v40, v41
	v_min_f32_e32 v41, v48, v42
	v_max_f32_e32 v42, v48, v42
	v_min_f32_e32 v48, v53, v52
	v_max_f32_e32 v52, v53, v52
	v_min_f32_e32 v53, v43, v49
	v_max_f32_e32 v43, v43, v49
	v_min_f32_e32 v49, v47, v54
	v_max_f32_e32 v47, v47, v54
	v_min_f32_e32 v54, v45, v44
	v_max_f32_e32 v44, v45, v44
	v_min_f32_e32 v45, v51, v46
	v_max_f32_e32 v46, v51, v46
	v_max_f32_e32 v51, v50, v56
	v_min_f32_e32 v50, v50, v56
	v_min_f32_e32 v84, v64, v70
	v_max_f32_e32 v64, v64, v70
	v_min_f32_e32 v70, v77, v72
	v_max_f32_e32 v72, v77, v72
	v_min_f32_e32 v77, v82, v81
	v_max_f32_e32 v81, v82, v81
	v_min_f32_e32 v82, v71, v78
	v_max_f32_e32 v71, v71, v78
	v_min_f32_e32 v78, v76, v83
	v_max_f32_e32 v76, v76, v83
	v_min_f32_e32 v83, v74, v73
	v_max_f32_e32 v73, v74, v73
	v_min_f32_e32 v74, v80, v75
	v_max_f32_e32 v75, v80, v75
	v_max_f32_e32 v80, v79, v85
	v_min_f32_e32 v79, v79, v85
	v_min_f32_e32 v19, v0, v2
	v_max_f32_e32 v0, v0, v2
	v_min_f32_e32 v2, v6, v8
	v_max_f32_e32 v6, v6, v8
	v_min_f32_e32 v8, v18, v7
	v_max_f32_e32 v7, v18, v7
	v_min_f32_e32 v18, v1, v16
	v_max_f32_e32 v1, v1, v16
	v_min_f32_e32 v16, v11, v10
	v_max_f32_e32 v10, v11, v10
	v_min_f32_e32 v11, v3, v4
	v_max_f32_e32 v3, v3, v4
	v_min_f32_e32 v4, v9, v5
	v_max_f32_e32 v5, v9, v5
	v_max_f32_e32 v9, v93, v17
	v_min_f32_e32 v17, v93, v17
	v_min_f32_e32 v39, v23, v29
	v_min_f32_e32 v38, v12, v20
	v_min_f32_e32 v37, v24, v30
	v_min_f32_e32 v36, v13, v21
	v_min_f32_e32 v35, v25, v31
	v_min_f32_e32 v34, v14, v22
	v_min_f32_e32 v33, v26, v28
	v_min_f32_e32 v32, v15, v27
	v_min_f32_e32 v56, v40, v42
	v_min_f32_e32 v57, v55, v41
	v_min_f32_e32 v58, v52, v43
	v_min_f32_e32 v59, v48, v53
	v_min_f32_e32 v60, v47, v44
	v_min_f32_e32 v61, v49, v54
	v_min_f32_e32 v62, v46, v51
	v_min_f32_e32 v63, v45, v50
	v_min_f32_e32 v85, v64, v72
	v_min_f32_e32 v86, v84, v70
	v_min_f32_e32 v87, v81, v71
	v_min_f32_e32 v88, v77, v82
	v_min_f32_e32 v89, v76, v73
	v_min_f32_e32 v90, v78, v83
	v_min_f32_e32 v91, v75, v80
	v_min_f32_e32 v92, v74, v79
	v_min_f32_e32 v93, v0, v6
	v_min_f32_e32 v94, v19, v2
	v_min_f32_e32 v95, v7, v1
	v_min_f32_e32 v96, v8, v18
	v_min_f32_e32 v97, v10, v3
	v_min_f32_e32 v98, v16, v11
	v_min_f32_e32 v99, v5, v9
	v_min_f32_e32 v100, v4, v17
	v_max3_f32 v23, v23, v29, v63
	v_max3_f32 v29, v39, v45, v50
	v_max3_f32 v12, v12, v20, v62
	v_max3_f32 v20, v38, v46, v51
	v_max3_f32 v24, v24, v30, v61
	v_max3_f32 v30, v37, v49, v54
	v_max3_f32 v13, v13, v21, v60
	v_max3_f32 v21, v36, v47, v44
	v_max3_f32 v25, v25, v31, v59
	v_max3_f32 v31, v35, v48, v53
	v_max3_f32 v14, v14, v22, v58
	v_max3_f32 v22, v34, v52, v43
	v_max3_f32 v26, v26, v28, v57
	v_max3_f32 v28, v33, v55, v41
	v_max3_f32 v15, v15, v27, v56
	v_max3_f32 v27, v32, v40, v42
	v_max3_f32 v40, v64, v72, v100
	v_max3_f32 v4, v85, v4, v17
	v_max3_f32 v17, v84, v70, v99
	v_max3_f32 v5, v86, v5, v9
	v_max3_f32 v9, v81, v71, v98
	v_max3_f32 v11, v87, v16, v11
	v_max3_f32 v16, v77, v82, v97
	v_max3_f32 v3, v88, v10, v3
	v_max3_f32 v10, v76, v73, v96
	v_max3_f32 v8, v89, v8, v18
	v_max3_f32 v18, v78, v83, v95
	v_max3_f32 v1, v90, v7, v1
	v_max3_f32 v7, v75, v80, v94
	v_max3_f32 v2, v91, v19, v2
	v_max3_f32 v19, v74, v79, v93
	v_max3_f32 v0, v92, v0, v6
	v_max_f32_e32 v32, v23, v25
	v_min_f32_e32 v23, v23, v25
	v_max_f32_e32 v25, v29, v31
	v_min_f32_e32 v29, v29, v31
	v_max_f32_e32 v31, v12, v14
	v_min_f32_e32 v12, v12, v14
	v_max_f32_e32 v14, v20, v22
	v_min_f32_e32 v20, v20, v22
	v_max_f32_e32 v22, v24, v26
	v_min_f32_e32 v24, v24, v26
	v_max_f32_e32 v26, v30, v28
	v_min_f32_e32 v28, v30, v28
	v_max_f32_e32 v30, v13, v15
	v_min_f32_e32 v13, v13, v15
	v_max_f32_e32 v15, v21, v27
	v_min_f32_e32 v21, v21, v27
	v_max_f32_e32 v6, v40, v10
	v_min_f32_e32 v10, v40, v10
	v_max_f32_e32 v40, v4, v8
	v_min_f32_e32 v4, v4, v8
	v_max_f32_e32 v8, v17, v18
	v_min_f32_e32 v17, v17, v18
	v_max_f32_e32 v18, v5, v1
	v_min_f32_e32 v1, v5, v1
	v_max_f32_e32 v5, v9, v7
	v_min_f32_e32 v7, v9, v7
	v_max_f32_e32 v9, v11, v2
	v_min_f32_e32 v2, v11, v2
	v_max_f32_e32 v11, v16, v19
	v_min_f32_e32 v16, v16, v19
	v_max_f32_e32 v19, v3, v0
	v_min_f32_e32 v0, v3, v0
	v_max_f32_e32 v27, v32, v22
	v_min_f32_e32 v22, v32, v22
	v_max_f32_e32 v32, v25, v26
	v_min_f32_e32 v25, v25, v26
	v_max_f32_e32 v26, v31, v30
	v_min_f32_e32 v30, v31, v30
	v_max_f32_e32 v31, v14, v15
	v_min_f32_e32 v14, v14, v15
	v_max_f32_e32 v15, v23, v24
	v_min_f32_e32 v23, v23, v24
	v_max_f32_e32 v24, v29, v28
	v_min_f32_e32 v28, v29, v28
	v_max_f32_e32 v29, v12, v13
	v_min_f32_e32 v12, v12, v13
	v_max_f32_e32 v13, v20, v21
	v_min_f32_e32 v20, v20, v21
	v_max_f32_e32 v3, v6, v5
	v_min_f32_e32 v5, v6, v5
	v_max_f32_e32 v6, v40, v9
	v_min_f32_e32 v9, v40, v9
	v_max_f32_e32 v40, v8, v11
	v_min_f32_e32 v8, v8, v11
	v_max_f32_e32 v11, v18, v19
	v_min_f32_e32 v18, v18, v19
	v_max_f32_e32 v19, v10, v7
	v_min_f32_e32 v7, v10, v7
	v_max_f32_e32 v10, v4, v2
	v_min_f32_e32 v2, v4, v2
	v_max_f32_e32 v4, v17, v16
	v_min_f32_e32 v16, v17, v16
	v_max_f32_e32 v17, v1, v0
	v_min_f32_e32 v0, v1, v0
	v_max_f32_e32 v21, v27, v26
	v_min_f32_e32 v26, v27, v26
	v_max_f32_e32 v27, v32, v31
	v_min_f32_e32 v31, v32, v31
	v_max_f32_e32 v32, v22, v30
	v_min_f32_e32 v22, v22, v30
	v_max_f32_e32 v30, v25, v14
	v_min_f32_e32 v14, v25, v14
	v_max_f32_e32 v25, v15, v29
	v_min_f32_e32 v15, v15, v29
	v_max_f32_e32 v29, v24, v13
	v_min_f32_e32 v13, v24, v13
	v_max_f32_e32 v24, v23, v12
	v_min_f32_e32 v12, v23, v12
	v_max_f32_e32 v23, v28, v20
	v_min_f32_e32 v20, v28, v20
	v_max_f32_e32 v1, v3, v40
	v_min_f32_e32 v3, v3, v40
	v_max_f32_e32 v40, v6, v11
	v_min_f32_e32 v6, v6, v11
	v_max_f32_e32 v11, v5, v8
	v_min_f32_e32 v5, v5, v8
	v_max_f32_e32 v8, v9, v18
	v_min_f32_e32 v9, v9, v18
	v_max_f32_e32 v18, v19, v4
	v_min_f32_e32 v4, v19, v4
	v_max_f32_e32 v19, v10, v17
	v_min_f32_e32 v10, v10, v17
	v_max_f32_e32 v17, v7, v16
	v_min_f32_e32 v7, v7, v16
	v_max_f32_e32 v16, v2, v0
	v_min_f32_e32 v0, v2, v0
	v_min_f32_e32 v28, v21, v27
	v_min_f32_e32 v33, v26, v31
	v_min_f32_e32 v34, v32, v30
	v_min_f32_e32 v35, v22, v14
	v_min_f32_e32 v36, v25, v29
	v_min_f32_e32 v37, v15, v13
	v_min_f32_e32 v38, v24, v23
	v_min_f32_e32 v39, v12, v20
	v_min_f32_e32 v2, v1, v40
	v_min_f32_e32 v41, v3, v6
	v_min_f32_e32 v42, v11, v8
	v_min_f32_e32 v43, v5, v9
	v_min_f32_e32 v44, v18, v19
	v_min_f32_e32 v45, v4, v10
	v_min_f32_e32 v46, v17, v16
	v_min_f32_e32 v47, v7, v0
	v_max3_f32 v21, v21, v27, v47
	v_max3_f32 v0, v28, v7, v0
	v_max3_f32 v7, v26, v31, v46
	v_max3_f32 v16, v33, v17, v16
	v_max3_f32 v17, v32, v30, v45
	v_max3_f32 v4, v34, v4, v10
	v_max3_f32 v10, v22, v14, v44
	v_max3_f32 v14, v35, v18, v19
	v_max3_f32 v18, v25, v29, v43
	v_max3_f32 v5, v36, v5, v9
	v_max3_f32 v9, v15, v13, v42
	v_max3_f32 v8, v37, v11, v8
	v_max3_f32 v11, v24, v23, v41
	v_max3_f32 v3, v38, v3, v6
	v_max3_f32 v2, v12, v20, v2
	v_max3_f32 v1, v39, v1, v40
	v_max_f32_e32 v6, v21, v18
	v_min_f32_e32 v12, v21, v18
	v_max_f32_e32 v13, v0, v5
	v_min_f32_e32 v0, v0, v5
	v_max_f32_e32 v5, v7, v9
	v_min_f32_e32 v7, v7, v9
	v_max_f32_e32 v9, v16, v8
	v_min_f32_e32 v8, v16, v8
	v_max_f32_e32 v15, v17, v11
	v_min_f32_e32 v11, v17, v11
	v_max_f32_e32 v16, v4, v3
	v_min_f32_e32 v3, v4, v3
	v_max_f32_e32 v4, v10, v2
	v_min_f32_e32 v2, v10, v2
	v_max_f32_e32 v10, v14, v1
	v_min_f32_e32 v1, v14, v1
	v_max_f32_e32 v14, v6, v15
	v_min_f32_e32 v6, v6, v15
	v_max_f32_e32 v15, v13, v16
	v_min_f32_e32 v13, v13, v16
	v_max_f32_e32 v16, v5, v4
	v_min_f32_e32 v4, v5, v4
	v_max_f32_e32 v5, v9, v10
	v_min_f32_e32 v9, v9, v10
	v_max_f32_e32 v10, v12, v11
	v_min_f32_e32 v11, v12, v11
	v_max_f32_e32 v12, v0, v3
	v_min_f32_e32 v0, v0, v3
	v_max_f32_e32 v3, v7, v2
	v_min_f32_e32 v2, v7, v2
	v_max_f32_e32 v7, v8, v1
	v_min_f32_e32 v1, v8, v1
	v_max_f32_e32 v17, v6, v4
	v_min_f32_e32 v6, v6, v4
	v_max_f32_e32 v4, v13, v9
	v_max_f32_e32 v18, v10, v3
	v_min_f32_e32 v3, v10, v3
	v_max_f32_e32 v10, v12, v7
	v_min_f32_e32 v7, v12, v7
	v_max_f32_e32 v8, v14, v16
	v_min_f32_e32 v14, v14, v16
	v_max_f32_e32 v16, v15, v5
	v_min_f32_e32 v15, v15, v5
	v_min_f32_e32 v9, v13, v9
	v_max_f32_e32 v19, v11, v2
	v_min_f32_e32 v2, v11, v2
	v_max_f32_e32 v11, v0, v1
	v_min_f32_e32 v23, v0, v1
	v_max_f32_e32 v20, v17, v4
	v_min_f32_e32 v4, v17, v4
	v_max_f32_e32 v17, v3, v7
	v_min_f32_e32 v3, v3, v7
	v_cndmask_b32_e32 v7, v66, v67, vcc
	v_max_f32_e32 v21, v8, v16
	v_min_f32_e32 v5, v8, v16
	v_max_f32_e32 v13, v14, v15
	v_min_f32_e32 v1, v14, v15
	v_max_f32_e32 v12, v6, v9
	v_min_f32_e32 v0, v6, v9
	v_max_f32_e32 v24, v18, v10
	v_min_f32_e32 v8, v18, v10
	v_max_f32_e32 v22, v19, v11
	v_min_f32_e32 v6, v19, v11
	v_max_f32_e32 v15, v2, v23
	v_min_f32_e32 v2, v2, v23
	v_lshlrev_b32_e32 v10, 2, v7
	ds_bpermute_b32 v29, v10, v2
	ds_bpermute_b32 v16, v10, v15
	ds_bpermute_b32 v25, v10, v6
	ds_bpermute_b32 v9, v10, v22
	ds_bpermute_b32 v28, v10, v3
	ds_bpermute_b32 v14, v10, v17
	ds_bpermute_b32 v23, v10, v8
	ds_bpermute_b32 v7, v10, v24
	ds_bpermute_b32 v31, v10, v0
	ds_bpermute_b32 v19, v10, v12
	ds_bpermute_b32 v27, v10, v4
	ds_bpermute_b32 v11, v10, v20
	ds_bpermute_b32 v30, v10, v1
	ds_bpermute_b32 v18, v10, v13
	ds_bpermute_b32 v26, v10, v5
	ds_bpermute_b32 v10, v10, v21
	v_cmp_gt_u32_e32 vcc, 32, v69
	s_and_saveexec_b64 s[14:15], vcc
	s_cbranch_execz .LBB0_1686
	s_waitcnt lgkmcnt(12)
	v_max_f32_e32 v9, v9, v9
	v_max_f32_e32 v1, v1, v1
	v_max_f32_e32 v9, v1, v9
	s_waitcnt lgkmcnt(4)
	v_max_f32_e32 v1, v11, v11
	v_max_f32_e32 v3, v3, v3
	v_max_f32_e32 v29, v29, v29
	v_max_f32_e32 v21, v21, v21
	v_max_f32_e32 v28, v28, v28
	v_max_f32_e32 v20, v20, v20
	v_max_f32_e32 v25, v25, v25
	v_max_f32_e32 v13, v13, v13
	v_max_f32_e32 v23, v23, v23
	v_max_f32_e32 v12, v12, v12
	v_max_f32_e32 v16, v16, v16
	v_max_f32_e32 v5, v5, v5
	v_max_f32_e32 v14, v14, v14
	v_max_f32_e32 v4, v4, v4
	v_max_f32_e32 v11, v3, v1
	v_max_f32_e32 v1, v7, v7
	v_max_f32_e32 v0, v0, v0
	v_max_f32_e32 v21, v21, v29
	v_max_f32_e32 v29, v31, v31
	v_max_f32_e32 v24, v24, v24
	v_max_f32_e32 v20, v20, v28
	s_waitcnt lgkmcnt(3)
	v_max_f32_e32 v28, v30, v30
	v_max_f32_e32 v22, v22, v22
	v_max_f32_e32 v13, v13, v25
	v_max_f32_e32 v25, v27, v27
	v_max_f32_e32 v17, v17, v17
	v_max_f32_e32 v12, v12, v23
	s_waitcnt lgkmcnt(1)
	v_max_f32_e32 v23, v26, v26
	v_max_f32_e32 v15, v15, v15
	v_max_f32_e32 v16, v5, v16
	v_max_f32_e32 v5, v19, v19
	v_max_f32_e32 v8, v8, v8
	v_max_f32_e32 v14, v4, v14
	v_max_f32_e32 v4, v18, v18
	v_max_f32_e32 v6, v6, v6
	v_max_f32_e32 v31, v0, v1
	s_waitcnt lgkmcnt(0)
	v_max_f32_e32 v0, v10, v10
	v_max_f32_e32 v1, v2, v2
	v_max_f32_e32 v24, v24, v29
	v_max_f32_e32 v22, v22, v28
	v_max_f32_e32 v17, v17, v25
	v_max_f32_e32 v15, v15, v23
	v_max_f32_e32 v8, v8, v5
	v_max_f32_e32 v18, v6, v4
	v_max_f32_e32 v10, v1, v0
	v_min_f32_e32 v29, v21, v24
	v_min_f32_e32 v28, v20, v22
	v_min_f32_e32 v25, v13, v17
	v_min_f32_e32 v23, v12, v15
	v_min_f32_e32 v5, v16, v8
	v_min_f32_e32 v4, v14, v18
	v_min_f32_e32 v19, v9, v11
	v_min_f32_e32 v7, v31, v10
	v_min_f32_e32 v30, v29, v28
	v_min_f32_e32 v26, v25, v23
	v_min_f32_e32 v6, v5, v4
	v_min_f32_e32 v0, v19, v7
	v_min_f32_e32 v27, v30, v26
	v_min_f32_e32 v1, v6, v0
	v_max_f32_e32 v26, v30, v26
	v_max_f32_e32 v0, v6, v0
	v_min_f32_e32 v3, v27, v1
	v_max_f32_e32 v2, v27, v1
	v_min_f32_e32 v1, v26, v0
	v_max_f32_e32 v0, v26, v0
	v_max_f32_e32 v26, v29, v28
	v_max_f32_e32 v23, v25, v23
	v_max_f32_e32 v4, v5, v4
	v_max_f32_e32 v5, v19, v7
	v_min_f32_e32 v6, v26, v23
	v_min_f32_e32 v19, v4, v5
	v_min_f32_e32 v7, v6, v19
	v_max_f32_e32 v6, v6, v19
	v_max_f32_e32 v19, v26, v23
	v_max_f32_e32 v4, v4, v5
	v_min_f32_e32 v5, v19, v4
	v_max_f32_e32 v4, v19, v4
	v_max_f32_e32 v19, v21, v24
	v_max_f32_e32 v20, v20, v22
	v_max_f32_e32 v13, v13, v17
	v_max_f32_e32 v12, v12, v15
	v_max_f32_e32 v16, v16, v8
	v_max_f32_e32 v14, v14, v18
	v_max_f32_e32 v18, v9, v11
	v_max_f32_e32 v22, v31, v10
	v_min_f32_e32 v21, v19, v20
	v_min_f32_e32 v15, v13, v12
	v_min_f32_e32 v8, v16, v14
	v_min_f32_e32 v9, v18, v22
	v_min_f32_e32 v17, v21, v15
	v_min_f32_e32 v10, v8, v9
	v_min_f32_e32 v11, v17, v10
	v_max_f32_e32 v10, v17, v10
	v_max_f32_e32 v17, v19, v20
	v_max_f32_e32 v12, v13, v12
	v_max_f32_e32 v16, v16, v14
	v_max_f32_e32 v18, v18, v22
	v_max_f32_e32 v15, v21, v15
	v_max_f32_e32 v8, v8, v9
	v_min_f32_e32 v13, v17, v12
	v_min_f32_e32 v14, v16, v18
	v_max_f32_e32 v12, v17, v12
	v_max_f32_e32 v16, v16, v18
	v_min_f32_e32 v9, v15, v8
	v_max_f32_e32 v8, v15, v8
	v_min_f32_e32 v15, v13, v14
	v_max_f32_e32 v14, v13, v14
	v_min_f32_e32 v13, v12, v16
	v_max_f32_e32 v12, v12, v16
	v_or_b32_e32 v16, s16, v69
	v_lshl_add_u32 v16, v16, 6, s36
	ds_write_b128 v16, v[12:15]
	ds_write_b128 v16, v[8:11] offset:16
	ds_write_b128 v16, v[4:7] offset:32
	ds_write_b128 v16, v[0:3] offset:48
	s_branch .LBB0_1686
